# MLA: tile write + next loads issued inside the MFMA-only segment; P2 GEMM loads hoisted
# speedup vs baseline: 1.0195x; 1.0048x over previous
.LBB0_288:
	s_and_b32 s17, s0, 1
	s_mul_i32 s21, s17, 0xd800
	s_add_i32 s21, s21, 0
	v_add3_u32 v156, s21, v112, v119
	v_add3_u32 v150, s21, v120, v119
	ds_read_b128 v[122:125], v156
	ds_read_b128 v[126:129], v150 offset:36864
	ds_read_b128 v[130:133], v150 offset:41472
	s_lshl_b64 s[22:23], s[84:85], 1
	v_lshl_add_u64 v[134:135], v[78:79], 0, s[22:23]
	s_waitcnt lgkmcnt(1)
	v_mfma_f32_32x32x16_bf16 v[0:15], v[122:125], v[126:129], v[0:15]
	v_lshl_add_u64 v[136:137], v[84:85], 0, s[22:23]
	v_lshl_add_u64 v[138:139], v[86:87], 0, s[22:23]
	v_lshl_add_u64 v[142:143], v[88:89], 0, s[22:23]
	v_lshl_add_u64 v[146:147], v[80:81], 0, s[22:23]
	v_lshl_add_u64 v[154:155], v[82:83], 0, s[22:23]
	global_load_dwordx4 v[158:161], v[134:135], off
	global_load_dwordx4 v[162:165], v[136:137], off
	global_load_dwordx4 v[166:169], v[138:139], off
	global_load_dwordx4 v[180:183], v[142:143], off
	global_load_dwordx4 v[184:187], v[146:147], off
	global_load_dwordx4 v[172:175], v[154:155], off
	s_xor_b32 s17, s17, 1
	s_add_i32 s0, s0, 1
	s_waitcnt lgkmcnt(0)
	v_mfma_f32_32x32x16_bf16 v[16:31], v[122:125], v[130:133], v[16:31]
	ds_read_b128 v[122:125], v156 offset:4608
	s_add_i32 s84, s84, 64
	s_mul_i32 s17, s17, 0xd800
	s_cmp_eq_u32 s1, s0
	s_waitcnt lgkmcnt(0)
	v_mfma_f32_32x32x16_bf16 v[32:47], v[122:125], v[126:129], v[32:47]
	v_mfma_f32_32x32x16_bf16 v[48:63], v[122:125], v[130:133], v[48:63]
	ds_read_b128 v[122:125], v156 offset:32
	ds_read_b128 v[126:129], v150 offset:36896
	ds_read_b128 v[130:133], v150 offset:41504
	s_waitcnt lgkmcnt(1)
	v_mfma_f32_32x32x16_bf16 v[0:15], v[122:125], v[126:129], v[0:15]
	s_waitcnt lgkmcnt(0)
	v_mfma_f32_32x32x16_bf16 v[16:31], v[122:125], v[130:133], v[16:31]
	ds_read_b128 v[122:125], v156 offset:4640
	s_waitcnt lgkmcnt(0)
	v_mfma_f32_32x32x16_bf16 v[32:47], v[122:125], v[126:129], v[32:47]
	v_mfma_f32_32x32x16_bf16 v[48:63], v[122:125], v[130:133], v[48:63]
	ds_read_b128 v[122:125], v156 offset:64
	ds_read_b128 v[126:129], v150 offset:36928
	ds_read_b128 v[130:133], v150 offset:41536
	s_waitcnt lgkmcnt(1)
	v_mfma_f32_32x32x16_bf16 v[0:15], v[122:125], v[126:129], v[0:15]
	s_waitcnt lgkmcnt(0)
	v_mfma_f32_32x32x16_bf16 v[16:31], v[122:125], v[130:133], v[16:31]
	ds_read_b128 v[122:125], v156 offset:4672
	s_waitcnt lgkmcnt(0)
	v_mfma_f32_32x32x16_bf16 v[32:47], v[122:125], v[126:129], v[32:47]
	s_nop 0
	s_nop 0
	v_mfma_f32_32x32x16_bf16 v[48:63], v[122:125], v[130:133], v[48:63]
	ds_read_b128 v[122:125], v156 offset:96
	ds_read_b128 v[130:133], v150 offset:36960
	s_nop 0
	ds_read_b128 v[150:153], v150 offset:41568
	s_waitcnt lgkmcnt(0)
	v_mfma_f32_32x32x16_bf16 v[0:15], v[122:125], v[130:133], v[0:15]
	v_mfma_f32_32x32x16_bf16 v[16:31], v[122:125], v[150:153], v[16:31]
	ds_read_b128 v[122:125], v156 offset:4704
	s_waitcnt lgkmcnt(0)
	v_mfma_f32_32x32x16_bf16 v[32:47], v[122:125], v[130:133], v[32:47]
	v_add_u32_e32 v154, s17, v121
	s_waitcnt vmcnt(0)
	ds_write_b128 v154, v[158:161]
	ds_write_b128 v154, v[162:165] offset:9216
	ds_write_b128 v154, v[166:169] offset:18432
	ds_write_b128 v154, v[180:183] offset:27648
	ds_write_b128 v154, v[184:187] offset:36864
	s_waitcnt lgkmcnt(0)
	ds_write_b128 v154, v[172:175] offset:46080
	v_mfma_f32_32x32x16_bf16 v[48:63], v[122:125], v[150:153], v[48:63]
	s_waitcnt lgkmcnt(0)
	s_barrier
	s_cbranch_scc0 .LBB0_288
	s_bitcmp1_b32 s1, 0
	s_cselect_b32 s0, 0xd800, 0
	s_add_i32 s0, s0, 0
	v_add3_u32 v112, s0, v112, v119
	v_add3_u32 v119, s0, v120, v119
	ds_read_b128 v[78:81], v112 offset:4608
	ds_read_b128 v[82:85], v119 offset:41472
	ds_read_b128 v[86:89], v112
	ds_read_b128 v[120:123], v112 offset:32
	ds_read_b128 v[124:127], v119 offset:36864
	ds_read_b128 v[128:131], v119 offset:36896
	s_waitcnt lgkmcnt(3)
	v_mfma_f32_32x32x16_bf16 v[16:31], v[86:89], v[82:85], v[16:31]
	s_mul_hi_i32 s0, s31, 0x3e0f83e1
	s_lshr_b32 s1, s0, 31
	s_ashr_i32 s0, s0, 11
	s_add_i32 s0, s0, s1
	s_mulk_i32 s0, 0x2100
	s_sub_i32 s0, s31, s0
	s_mov_b64 s[22:23], -1
	s_waitcnt lgkmcnt(1)
	v_mfma_f32_32x32x16_bf16 v[0:15], v[86:89], v[124:127], v[0:15]
	s_and_b64 vcc, exec, s[18:19]
	v_mfma_f32_32x32x16_bf16 v[32:47], v[78:81], v[124:127], v[32:47]
	v_mfma_f32_32x32x16_bf16 v[48:63], v[78:81], v[82:85], v[48:63]
	ds_read_b128 v[78:81], v112 offset:4640
	ds_read_b128 v[82:85], v119 offset:41504
	s_waitcnt lgkmcnt(2)
	v_mfma_f32_32x32x16_bf16 v[0:15], v[120:123], v[128:131], v[0:15]
	s_waitcnt lgkmcnt(0)
	v_mfma_f32_32x32x16_bf16 v[16:31], v[120:123], v[82:85], v[16:31]
	v_mfma_f32_32x32x16_bf16 v[32:47], v[78:81], v[128:131], v[32:47]
	v_mfma_f32_32x32x16_bf16 v[48:63], v[78:81], v[82:85], v[48:63]
	ds_read_b128 v[78:81], v112 offset:64
	ds_read_b128 v[82:85], v112 offset:4672
	ds_read_b128 v[86:89], v119 offset:36928
	ds_read_b128 v[120:123], v119 offset:41536
	s_waitcnt lgkmcnt(1)
	v_mfma_f32_32x32x16_bf16 v[0:15], v[78:81], v[86:89], v[0:15]
	s_waitcnt lgkmcnt(0)
	v_mfma_f32_32x32x16_bf16 v[16:31], v[78:81], v[120:123], v[16:31]
	v_mfma_f32_32x32x16_bf16 v[32:47], v[82:85], v[86:89], v[32:47]
	v_mfma_f32_32x32x16_bf16 v[48:63], v[82:85], v[120:123], v[48:63]
	ds_read_b128 v[78:81], v112 offset:96
	ds_read_b128 v[82:85], v112 offset:4704
	ds_read_b128 v[86:89], v119 offset:36960
	ds_read_b128 v[120:123], v119 offset:41568
	s_waitcnt lgkmcnt(0)
	s_barrier
	v_mfma_f32_32x32x16_bf16 v[0:15], v[78:81], v[86:89], v[0:15]
	v_mfma_f32_32x32x16_bf16 v[16:31], v[78:81], v[120:123], v[16:31]
	v_mov_b32_e32 v78, v170
	s_nop 0
	v_lshrrev_b32_e32 v81, 1, v78
	v_and_b32_e32 v79, 64, v78
	v_and_b32_e32 v80, 31, v78
	v_and_b32_e32 v81, 0xfffffc0, v81
	v_lshrrev_b32_e32 v78, 3, v78
	v_and_or_b32 v78, v78, 4, v81
	v_lshl_add_u32 v79, v79, 2, 0
	v_lshlrev_b32_e32 v80, 2, v80
	v_mul_lo_u32 v78, v78, s34
	v_add3_u32 v78, v79, v80, v78
	ds_write2_b32 v78, v0, v16 offset1:32
	ds_write2_b32 v78, v1, v17 offset0:132 offset1:164
	v_add_u32_e32 v0, 0x400, v78
	ds_write2_b32 v0, v2, v18 offset0:8 offset1:40
	ds_write2_b32 v0, v3, v19 offset0:140 offset1:172
	v_add_u32_e32 v0, 0x1000, v78
	v_mfma_f32_32x32x16_bf16 v[32:47], v[82:85], v[86:89], v[32:47]
	ds_write2_b32 v0, v4, v20 offset0:32 offset1:64
	ds_write2_b32 v0, v5, v21 offset0:164 offset1:196
	v_add_u32_e32 v0, 0x1400, v78
	ds_write2_b32 v0, v6, v22 offset0:40 offset1:72
	ds_write2_b32 v0, v7, v23 offset0:172 offset1:204
	v_add_u32_e32 v0, 0x2000, v78
	ds_write2_b32 v0, v8, v24 offset0:64 offset1:96
	ds_write2_b32 v0, v9, v25 offset0:196 offset1:228
	v_add_u32_e32 v0, 0x2400, v78
	ds_write2_b32 v0, v10, v26 offset0:72 offset1:104
	ds_write2_b32 v0, v11, v27 offset0:204 offset1:236
	v_mfma_f32_32x32x16_bf16 v[48:63], v[82:85], v[120:123], v[48:63]
	v_add_u32_e32 v0, 0x3000, v78
	ds_write2_b32 v0, v12, v28 offset0:96 offset1:128
	v_add_u32_e32 v0, 0x3200, v78
	ds_write2_b32 v0, v13, v29 offset0:100 offset1:132
	v_add_u32_e32 v0, 0x3400, v78
	ds_write2_b32 v0, v14, v30 offset0:104 offset1:136
	v_add_u32_e32 v0, 0x3600, v78
	ds_write2_b32 v0, v15, v31 offset0:108 offset1:140
	v_add_u32_e32 v0, 0x4000, v78
	s_nop 2
	ds_write2_b32 v0, v32, v48 offset0:128 offset1:160
	v_add_u32_e32 v0, 0x4400, v78
	ds_write2_b32 v0, v33, v49 offset0:4 offset1:36
	ds_write2_b32 v0, v34, v50 offset0:136 offset1:168
	v_add_u32_e32 v0, 0x4800, v78
	ds_write2_b32 v0, v35, v51 offset0:12 offset1:44
	v_add_u32_e32 v0, 0x5000, v78
	ds_write2_b32 v0, v36, v52 offset0:160 offset1:192
	v_add_u32_e32 v0, 0x5400, v78
	ds_write2_b32 v0, v37, v53 offset0:36 offset1:68
	ds_write2_b32 v0, v38, v54 offset0:168 offset1:200
	v_add_u32_e32 v0, 0x5800, v78
	ds_write2_b32 v0, v39, v55 offset0:44 offset1:76
	v_add_u32_e32 v0, 0x6000, v78
	ds_write2_b32 v0, v40, v56 offset0:192 offset1:224
	v_add_u32_e32 v0, 0x6400, v78
	ds_write2_b32 v0, v41, v57 offset0:68 offset1:100
	ds_write2_b32 v0, v42, v58 offset0:200 offset1:232
	v_add_u32_e32 v0, 0x6800, v78
	ds_write2_b32 v0, v43, v59 offset0:76 offset1:108
	v_add_u32_e32 v0, 0x7200, v78
	ds_write2_b32 v0, v44, v60 offset0:96 offset1:128
	v_add_u32_e32 v0, 0x7400, v78
	ds_write2_b32 v0, v45, v61 offset0:100 offset1:132
	v_add_u32_e32 v0, 0x7600, v78
	ds_write2_b32 v0, v46, v62 offset0:104 offset1:136
	v_add_u32_e32 v0, 0x7800, v78
	ds_write2_b32 v0, v47, v63 offset0:108 offset1:140
	s_waitcnt lgkmcnt(0)
	s_barrier
	s_cbranch_vccz .LBB0_291
	ds_read_b32 v8, v98
	ds_read_b128 v[0:3], v115
	ds_read_b128 v[4:7], v115 offset:16
	s_mul_hi_i32 s1, s30, 0x8dda5203
	s_add_i32 s1, s1, s30
	s_lshr_b32 s17, s1, 31
	s_waitcnt lgkmcnt(1)
	v_pk_mul_f32 v[0:1], v[8:9], v[0:1] op_sel_hi:[0,1]
	v_pk_mul_f32 v[2:3], v[8:9], v[2:3] op_sel_hi:[0,1]
	s_waitcnt lgkmcnt(0)
	v_pk_mul_f32 v[4:5], v[8:9], v[4:5] op_sel_hi:[0,1]
	v_cvt_pk_bf16_f32 v0, v0, v1
	v_cvt_pk_bf16_f32 v1, v2, v3
	v_cvt_pk_bf16_f32 v2, v4, v5
	v_add_u32_e32 v4, s31, v97
	s_lshr_b32 s1, s1, 8
	s_mov_b32 s21, s85
	v_ashrrev_i32_e32 v5, 31, v4
	s_add_i32 s1, s1, s17
	v_pk_mul_f32 v[6:7], v[8:9], v[6:7] op_sel_hi:[0,1]
	v_lshl_add_u64 v[4:5], v[4:5], 3, s[20:21]
	s_movk_i32 s17, 0xc0
	v_cvt_pk_bf16_f32 v3, v6, v7
	v_mad_u64_u32 v[6:7], s[18:19], v4, s17, v[68:69]
	v_mad_i32_i24 v7, v5, s17, v7
	global_store_dwordx4 v[6:7], v[0:3], off
	ds_read_b32 v8, v100
	ds_read_b128 v[0:3], v116
	ds_read_b128 v[4:7], v116 offset:16
	s_lshl_b32 s1, s1, 9
	s_mov_b64 s[22:23], 0
	s_waitcnt lgkmcnt(0)
	v_pk_mul_f32 v[0:1], v[8:9], v[0:1] op_sel_hi:[0,1]
	v_pk_mul_f32 v[2:3], v[8:9], v[2:3] op_sel_hi:[0,1]
	v_pk_mul_f32 v[4:5], v[8:9], v[4:5] op_sel_hi:[0,1]
	v_cvt_pk_bf16_f32 v0, v0, v1
	v_cvt_pk_bf16_f32 v1, v2, v3
	v_cvt_pk_bf16_f32 v2, v4, v5
	v_add_u32_e32 v4, s31, v99
	v_ashrrev_i32_e32 v5, 31, v4
	v_pk_mul_f32 v[6:7], v[8:9], v[6:7] op_sel_hi:[0,1]
	v_lshl_add_u64 v[4:5], v[4:5], 3, s[20:21]
	v_cvt_pk_bf16_f32 v3, v6, v7
	v_mad_u64_u32 v[6:7], s[18:19], v4, s17, v[68:69]
	v_mad_i32_i24 v7, v5, s17, v7
	global_store_dwordx4 v[6:7], v[0:3], off
	ds_read_b32 v8, v102
	ds_read_b128 v[0:3], v117
	ds_read_b128 v[4:7], v117 offset:16
	s_waitcnt lgkmcnt(0)
	v_pk_mul_f32 v[0:1], v[8:9], v[0:1] op_sel_hi:[0,1]
	v_pk_mul_f32 v[2:3], v[8:9], v[2:3] op_sel_hi:[0,1]
	v_pk_mul_f32 v[4:5], v[8:9], v[4:5] op_sel_hi:[0,1]
	v_cvt_pk_bf16_f32 v0, v0, v1
	v_cvt_pk_bf16_f32 v1, v2, v3
	v_cvt_pk_bf16_f32 v2, v4, v5
	v_add_u32_e32 v4, s31, v101
	v_ashrrev_i32_e32 v5, 31, v4
	v_pk_mul_f32 v[6:7], v[8:9], v[6:7] op_sel_hi:[0,1]
	v_lshl_add_u64 v[4:5], v[4:5], 3, s[20:21]
	v_cvt_pk_bf16_f32 v3, v6, v7
	v_mad_u64_u32 v[6:7], s[18:19], v4, s17, v[68:69]
	v_mad_i32_i24 v7, v5, s17, v7
	global_store_dwordx4 v[6:7], v[0:3], off
	ds_read_b32 v8, v104
	ds_read_b128 v[0:3], v118
	ds_read_b128 v[4:7], v118 offset:16
	s_waitcnt lgkmcnt(0)
	v_pk_mul_f32 v[0:1], v[8:9], v[0:1] op_sel_hi:[0,1]
	v_pk_mul_f32 v[2:3], v[8:9], v[2:3] op_sel_hi:[0,1]
	v_pk_mul_f32 v[4:5], v[8:9], v[4:5] op_sel_hi:[0,1]
	v_cvt_pk_bf16_f32 v0, v0, v1
	v_cvt_pk_bf16_f32 v1, v2, v3
	v_cvt_pk_bf16_f32 v2, v4, v5
	v_add_u32_e32 v4, s31, v103
	v_ashrrev_i32_e32 v5, 31, v4
	v_pk_mul_f32 v[6:7], v[8:9], v[6:7] op_sel_hi:[0,1]
	v_lshl_add_u64 v[4:5], v[4:5], 3, s[20:21]
	v_cvt_pk_bf16_f32 v3, v6, v7
	v_mad_u64_u32 v[6:7], s[18:19], v4, s17, v[68:69]
	v_mad_i32_i24 v7, v5, s17, v7
	s_lshl_b32 s17, s20, 6
	s_add_i32 s17, s17, s1
	global_store_dwordx4 v[6:7], v[0:3], off
	s_ashr_i32 s1, s0, 31
	s_nop 0
	v_or_b32_e32 v2, s17, v96
	v_mov_b64_e32 v[0:1], s[14:15]
	v_mad_i64_i32 v[0:1], s[18:19], v2, s39, v[0:1]
	ds_read2_b32 v[10:11], v105 offset0:64 offset1:196
	ds_read_b128 v[2:5], v106
	ds_read_b128 v[6:9], v106 offset:16
	v_lshl_add_u64 v[0:1], s[0:1], 1, v[0:1]
	s_waitcnt lgkmcnt(0)
	v_pk_mul_f32 v[2:3], v[10:11], v[2:3]
	v_add_u32_e32 v10, 0x400, v105
	ds_read2_b32 v[10:11], v10 offset0:72 offset1:204
	v_cvt_pk_bf16_f32 v2, v2, v3
	s_waitcnt lgkmcnt(0)
	v_pk_mul_f32 v[4:5], v[10:11], v[4:5]
	v_add_u32_e32 v10, 0x800, v105
	ds_read2_b32 v[10:11], v10 offset0:80 offset1:212
	v_cvt_pk_bf16_f32 v3, v4, v5
	s_waitcnt lgkmcnt(0)
	v_pk_mul_f32 v[6:7], v[10:11], v[6:7]
	v_add_u32_e32 v10, 0xc00, v105
	ds_read2_b32 v[10:11], v10 offset0:88 offset1:220
	v_cvt_pk_bf16_f32 v4, v6, v7
	v_lshl_add_u64 v[6:7], v[70:71], 1, v[0:1]
	s_waitcnt lgkmcnt(0)
	v_pk_mul_f32 v[8:9], v[10:11], v[8:9]
	s_nop 0
	v_cvt_pk_bf16_f32 v5, v8, v9
	global_store_dwordx4 v[6:7], v[2:5], off
	ds_read2_b32 v[10:11], v107 offset0:64 offset1:196
	ds_read_b128 v[2:5], v108
	ds_read_b128 v[6:9], v108 offset:16
	s_waitcnt lgkmcnt(0)
	v_pk_mul_f32 v[2:3], v[10:11], v[2:3]
	v_add_u32_e32 v10, 0x400, v107
	ds_read2_b32 v[10:11], v10 offset0:72 offset1:204
	v_cvt_pk_bf16_f32 v2, v2, v3
	s_waitcnt lgkmcnt(0)
	v_pk_mul_f32 v[4:5], v[10:11], v[4:5]
	v_add_u32_e32 v10, 0x800, v107
	ds_read2_b32 v[10:11], v10 offset0:80 offset1:212
	v_cvt_pk_bf16_f32 v3, v4, v5
	s_waitcnt lgkmcnt(0)
	v_pk_mul_f32 v[6:7], v[10:11], v[6:7]
	v_add_u32_e32 v10, 0xc00, v107
	ds_read2_b32 v[10:11], v10 offset0:88 offset1:220
	v_cvt_pk_bf16_f32 v4, v6, v7
	v_lshl_add_u64 v[6:7], v[72:73], 1, v[0:1]
	s_waitcnt lgkmcnt(0)
	v_pk_mul_f32 v[8:9], v[10:11], v[8:9]
	s_nop 0
	v_cvt_pk_bf16_f32 v5, v8, v9
	global_store_dwordx4 v[6:7], v[2:5], off
	ds_read2_b32 v[10:11], v109 offset0:64 offset1:196
	ds_read_b128 v[2:5], v110
	ds_read_b128 v[6:9], v110 offset:16
	s_waitcnt lgkmcnt(0)
	v_pk_mul_f32 v[2:3], v[10:11], v[2:3]
	v_add_u32_e32 v10, 0x400, v109
	ds_read2_b32 v[10:11], v10 offset0:72 offset1:204
	v_cvt_pk_bf16_f32 v2, v2, v3
	s_waitcnt lgkmcnt(0)
	v_pk_mul_f32 v[4:5], v[10:11], v[4:5]
	v_add_u32_e32 v10, 0x800, v109
	ds_read2_b32 v[10:11], v10 offset0:80 offset1:212
	v_cvt_pk_bf16_f32 v3, v4, v5
	s_waitcnt lgkmcnt(0)
	v_pk_mul_f32 v[6:7], v[10:11], v[6:7]
	v_add_u32_e32 v10, 0xc00, v109
	ds_read2_b32 v[10:11], v10 offset0:88 offset1:220
	v_cvt_pk_bf16_f32 v4, v6, v7
	v_lshl_add_u64 v[6:7], v[74:75], 1, v[0:1]
	v_lshl_add_u64 v[0:1], v[76:77], 1, v[0:1]
	s_waitcnt lgkmcnt(0)
	v_pk_mul_f32 v[8:9], v[10:11], v[8:9]
	s_nop 0
	v_cvt_pk_bf16_f32 v5, v8, v9
	global_store_dwordx4 v[6:7], v[2:5], off
	ds_read2_b32 v[10:11], v111 offset0:64 offset1:196
	ds_read_b128 v[2:5], v114
	ds_read_b128 v[6:9], v114 offset:16
	s_waitcnt lgkmcnt(0)
	v_pk_mul_f32 v[2:3], v[10:11], v[2:3]
	v_add_u32_e32 v10, 0x400, v111
	ds_read2_b32 v[10:11], v10 offset0:72 offset1:204
	v_cvt_pk_bf16_f32 v2, v2, v3
	s_waitcnt lgkmcnt(0)
	v_pk_mul_f32 v[4:5], v[10:11], v[4:5]
	v_add_u32_e32 v10, 0x800, v111
	ds_read2_b32 v[10:11], v10 offset0:80 offset1:212
	v_cvt_pk_bf16_f32 v3, v4, v5
	s_waitcnt lgkmcnt(0)
	v_pk_mul_f32 v[6:7], v[10:11], v[6:7]
	v_add_u32_e32 v10, 0xc00, v111
	ds_read2_b32 v[10:11], v10 offset0:88 offset1:220
	v_cvt_pk_bf16_f32 v4, v6, v7
	s_waitcnt lgkmcnt(0)
	v_pk_mul_f32 v[8:9], v[10:11], v[8:9]
	s_nop 0
	v_cvt_pk_bf16_f32 v5, v8, v9
	global_store_dwordx4 v[0:1], v[2:5], off

.Lmla_nopv_A:
	s_waitcnt lgkmcnt(11)
	v_mfma_f32_32x32x16_bf16 v[64:79], v[48:51], v[80:83], v[32:47]
	s_waitcnt lgkmcnt(10)
	v_mfma_f32_32x32x16_bf16 v[48:63], v[122:125], v[80:83], v[32:47]
	s_waitcnt lgkmcnt(9)
	v_mfma_f32_32x32x16_bf16 v[64:79], v[118:121], v[84:87], v[64:79]
	s_waitcnt lgkmcnt(8)
	v_mfma_f32_32x32x16_bf16 v[48:63], v[126:129], v[84:87], v[48:63]
	s_waitcnt lgkmcnt(7)
	v_mfma_f32_32x32x16_bf16 v[64:79], v[130:133], v[88:91], v[64:79]
	s_waitcnt lgkmcnt(6)
	v_mfma_f32_32x32x16_bf16 v[48:63], v[138:141], v[88:91], v[48:63]
	s_waitcnt lgkmcnt(5)
	v_mfma_f32_32x32x16_bf16 v[64:79], v[134:137], v[92:95], v[64:79]
	s_waitcnt lgkmcnt(4)
	v_mfma_f32_32x32x16_bf16 v[48:63], v[142:145], v[92:95], v[48:63]
	s_waitcnt lgkmcnt(3)
	v_mfma_f32_32x32x16_bf16 v[64:79], v[146:149], v[96:99], v[64:79]
	ds_read_b128 v[202:205], v177 offset:26624
	ds_read_b128 v[206:209], v177 offset:26656
	ds_read_b128 v[218:221], v177 offset:31232
	ds_read_b128 v[222:225], v177 offset:31264
	ds_read_b128 v[210:213], v177 offset:26688
	ds_read_b128 v[214:217], v177 offset:26720
	ds_read_b128 v[226:229], v177 offset:31296
	ds_read_b128 v[230:233], v177 offset:31328
	s_waitcnt lgkmcnt(10)
	v_mfma_f32_32x32x16_bf16 v[48:63], v[194:197], v[96:99], v[48:63]
	s_add_i32 s12, s28, 1
	s_cmp_ge_i32 s12, s22
	s_cbranch_scc1 .Lmla_nowrite_A
	s_and_b32 s12, s12, 1
	s_mul_i32 s13, s12, 0x3400
	v_add3_u32 v172, s13, v165, v166
	s_waitcnt vmcnt(0)
	ds_write_b128 v172, v[104:107]
	v_add3_u32 v172, s13, v167, v168
	ds_write_b128 v172, v[108:111]
	s_mulk_i32 s12, 0x2400
	v_add_u32_e32 v172, s12, v169
	v_add_u32_e32 v172, 0x6800, v172
	ds_write2_b64 v172, v[114:115], v[116:117] offset1:2
	s_add_i32 s12, s28, 2
	s_cmp_ge_i32 s12, s22
	s_cbranch_scc1 .Lmla_nowrite_A
	s_nop 1
	global_load_dwordx4 v[104:107], v[150:151], off
	global_load_dwordx4 v[108:111], v[154:155], off
	global_load_dwordx4 v[114:117], v[152:153], off
	v_lshl_add_u64 v[150:151], v[150:151], 0, s[26:27]
	v_lshl_add_u64 v[154:155], v[154:155], 0, s[26:27]
	v_lshl_add_u64 v[152:153], v[152:153], 0, s[30:31]
.Lmla_nowrite_A:
	s_waitcnt lgkmcnt(9)
	v_mfma_f32_32x32x16_bf16 v[64:79], v[178:181], v[100:103], v[64:79]
	s_waitcnt lgkmcnt(8)
	v_mfma_f32_32x32x16_bf16 v[48:63], v[198:201], v[100:103], v[48:63]
	s_setprio 0
	s_nop 10
	v_max_f32_e32 v172, v64, v65
	v_max3_f32 v173, v66, v67, v49
	v_max3_f32 v172, v172, v48, v50
	v_max3_f32 v172, v172, v51, v68
	v_max3_f32 v173, v173, v70, v71
	v_max3_f32 v172, v172, v69, v52
	v_max3_f32 v173, v173, v54, v55
	s_nop 1
	v_max3_f32 v172, v172, v53, v72
	v_max3_f32 v173, v173, v74, v75
	v_max3_f32 v172, v172, v73, v56
	v_max3_f32 v173, v173, v58, v59
	v_max3_f32 v172, v172, v57, v76
	v_max3_f32 v173, v173, v78, v79
	v_max3_f32 v172, v172, v77, v60
	s_nop 1
	v_max3_f32 v173, v173, v62, v63
	v_max3_f32 v172, v172, v61, v173
	v_mov_b32_e32 v173, v172
	s_nop 1
	v_permlane32_swap_b32_e32 v172, v173
	v_max_f32_e32 v177, v172, v173
	v_cmp_lt_f32_e32 vcc, s14, v177
	s_cbranch_vccz .Lmla_norescale_A
	v_max_f32_e32 v172, s15, v177
	v_max_f32_e32 v173, 0xc2c80000, v172
	v_exp_f32_e64 v173, -v173
	v_add_f32_e32 v156, v156, v172
	v_sub_f32_e32 v48, v48, v172
	v_sub_f32_e32 v49, v49, v172
	s_nop 1
	v_sub_f32_e32 v50, v50, v172
	v_sub_f32_e32 v51, v51, v172
	v_sub_f32_e32 v52, v52, v172
	v_sub_f32_e32 v53, v53, v172
	v_sub_f32_e32 v54, v54, v172
	v_sub_f32_e32 v55, v55, v172
	v_sub_f32_e32 v56, v56, v172
	s_nop 1
	v_sub_f32_e32 v57, v57, v172
	v_sub_f32_e32 v58, v58, v172
	v_sub_f32_e32 v59, v59, v172
	v_sub_f32_e32 v60, v60, v172
	v_sub_f32_e32 v61, v61, v172
	v_sub_f32_e32 v62, v62, v172
	v_sub_f32_e32 v63, v63, v172
	s_nop 1
	v_sub_f32_e32 v64, v64, v172
	v_sub_f32_e32 v65, v65, v172
	v_sub_f32_e32 v66, v66, v172
	v_sub_f32_e32 v67, v67, v172
	v_sub_f32_e32 v68, v68, v172
	v_sub_f32_e32 v69, v69, v172
	v_sub_f32_e32 v70, v70, v172
	s_nop 1
	v_sub_f32_e32 v71, v71, v172
	v_sub_f32_e32 v72, v72, v172
	v_sub_f32_e32 v73, v73, v172
	v_sub_f32_e32 v74, v74, v172
	v_sub_f32_e32 v75, v75, v172
	v_sub_f32_e32 v76, v76, v172
	v_sub_f32_e32 v77, v77, v172
	s_nop 1
	v_sub_f32_e32 v78, v78, v172
	v_sub_f32_e32 v79, v79, v172
	v_mul_f32_e32 v0, v0, v173
	v_mul_f32_e32 v1, v1, v173
	v_mul_f32_e32 v2, v2, v173
	v_mul_f32_e32 v3, v3, v173
	v_mul_f32_e32 v4, v4, v173
	s_nop 1
	v_mul_f32_e32 v5, v5, v173
	v_mul_f32_e32 v6, v6, v173
	v_mul_f32_e32 v7, v7, v173
	v_mul_f32_e32 v8, v8, v173
	v_mul_f32_e32 v9, v9, v173
	v_mul_f32_e32 v10, v10, v173
	v_mul_f32_e32 v11, v11, v173
	s_nop 1
	v_mul_f32_e32 v12, v12, v173
	v_mul_f32_e32 v13, v13, v173
	v_mul_f32_e32 v14, v14, v173
	v_mul_f32_e32 v15, v15, v173
	v_mul_f32_e32 v16, v16, v173
	v_mul_f32_e32 v17, v17, v173
	v_mul_f32_e32 v18, v18, v173
	s_nop 1
	v_mul_f32_e32 v19, v19, v173
	v_mul_f32_e32 v20, v20, v173
	v_mul_f32_e32 v21, v21, v173
	v_mul_f32_e32 v22, v22, v173
	v_mul_f32_e32 v23, v23, v173
	v_mul_f32_e32 v24, v24, v173
	v_mul_f32_e32 v25, v25, v173
	s_nop 1
	v_mul_f32_e32 v26, v26, v173
	v_mul_f32_e32 v27, v27, v173
	v_mul_f32_e32 v28, v28, v173
	v_mul_f32_e32 v29, v29, v173
	v_mul_f32_e32 v30, v30, v173
	v_mul_f32_e32 v31, v31, v173
	v_mul_f32_e32 v157, v157, v173
	s_nop 1
	v_sub_f32_e32 v32, 0, v156
	v_mov_b32_e32 v33, v32
	v_mov_b32_e32 v34, v32
	v_mov_b32_e32 v35, v32
	v_mov_b32_e32 v36, v32
	v_mov_b32_e32 v37, v32
	v_mov_b32_e32 v38, v32
	s_nop 1
	v_mov_b32_e32 v39, v32
	v_mov_b32_e32 v40, v32
	v_mov_b32_e32 v41, v32
	v_mov_b32_e32 v42, v32
	v_mov_b32_e32 v43, v32
	v_mov_b32_e32 v44, v32
	v_mov_b32_e32 v45, v32
	s_nop 1
	v_mov_b32_e32 v46, v32
	v_mov_b32_e32 v47, v32

.Lmla_B_entry:
	s_and_b32 s12, s28, 1
	s_mul_i32 s13, s12, 0x3400
	v_add_u32_e32 v52, s13, v112
	ds_read_b128 v[48:51], v52
	ds_read_b128 v[122:125], v52 offset:6656
	ds_read_b128 v[118:121], v52 offset:32
	ds_read_b128 v[126:129], v52 offset:6688
	ds_read_b128 v[130:133], v52 offset:64
	ds_read_b128 v[138:141], v52 offset:6720
	ds_read_b128 v[134:137], v52 offset:96
	ds_read_b128 v[142:145], v52 offset:6752
	ds_read_b128 v[146:149], v52 offset:128
	ds_read_b128 v[194:197], v52 offset:6784
	ds_read_b128 v[178:181], v52 offset:160
	ds_read_b128 v[198:201], v52 offset:6816
	s_mul_i32 s13, s12, 0x2400
	v_add_u32_e32 v177, s13, v176
	s_setprio 3
	s_waitcnt lgkmcnt(11)
	v_mfma_f32_32x32x16_bf16 v[64:79], v[48:51], v[80:83], v[32:47]
	s_waitcnt lgkmcnt(10)
	v_mfma_f32_32x32x16_bf16 v[48:63], v[122:125], v[80:83], v[32:47]
	s_waitcnt lgkmcnt(9)
	v_mfma_f32_32x32x16_bf16 v[64:79], v[118:121], v[84:87], v[64:79]
	s_waitcnt lgkmcnt(8)
	v_mfma_f32_32x32x16_bf16 v[48:63], v[126:129], v[84:87], v[48:63]
	s_waitcnt lgkmcnt(7)
	v_mfma_f32_32x32x16_bf16 v[64:79], v[130:133], v[88:91], v[64:79]
	s_waitcnt lgkmcnt(6)
	v_mfma_f32_32x32x16_bf16 v[48:63], v[138:141], v[88:91], v[48:63]
	s_waitcnt lgkmcnt(5)
	v_mfma_f32_32x32x16_bf16 v[64:79], v[134:137], v[92:95], v[64:79]
	s_waitcnt lgkmcnt(4)
	v_mfma_f32_32x32x16_bf16 v[48:63], v[142:145], v[92:95], v[48:63]
	s_waitcnt lgkmcnt(3)
	v_mfma_f32_32x32x16_bf16 v[64:79], v[146:149], v[96:99], v[64:79]
	ds_read_b128 v[202:205], v177 offset:26624
	ds_read_b128 v[206:209], v177 offset:26656
	ds_read_b128 v[218:221], v177 offset:31232
	ds_read_b128 v[222:225], v177 offset:31264
	ds_read_b128 v[210:213], v177 offset:26688
	ds_read_b128 v[214:217], v177 offset:26720
	ds_read_b128 v[226:229], v177 offset:31296
	ds_read_b128 v[230:233], v177 offset:31328
	s_waitcnt lgkmcnt(10)
	v_mfma_f32_32x32x16_bf16 v[48:63], v[194:197], v[96:99], v[48:63]
	s_add_i32 s12, s28, 1
	s_cmp_ge_i32 s12, s22
	s_cbranch_scc1 .Lmla_nowrite_B0
	s_and_b32 s12, s12, 1
	s_mul_i32 s13, s12, 0x3400
	v_add3_u32 v172, s13, v165, v166
	s_waitcnt vmcnt(0)
	ds_write_b128 v172, v[104:107]
	s_mulk_i32 s12, 0x2400
	v_add_u32_e32 v172, s12, v169
	v_add_u32_e32 v172, 0x6800, v172
	ds_write2_b64 v172, v[114:115], v[116:117] offset1:2
	s_add_i32 s12, s28, 2
	s_cmp_ge_i32 s12, s22
	s_cbranch_scc1 .Lmla_nowrite_B0
	s_nop 1
	global_load_dwordx4 v[104:107], v[150:151], off
	global_load_dwordx4 v[114:117], v[152:153], off
	v_lshl_add_u64 v[150:151], v[150:151], 0, s[26:27]
	v_lshl_add_u64 v[152:153], v[152:153], 0, s[30:31]
.Lmla_nowrite_B0:
	s_waitcnt lgkmcnt(9)
	v_mfma_f32_32x32x16_bf16 v[64:79], v[178:181], v[100:103], v[64:79]
	s_waitcnt lgkmcnt(8)
	v_mfma_f32_32x32x16_bf16 v[48:63], v[198:201], v[100:103], v[48:63]
	s_setprio 0
	s_waitcnt lgkmcnt(0)
	s_barrier
	s_mov_b32 s28, 1
	s_cmp_lt_i32 s28, s22
	s_cbranch_scc0 .Lmla_B_tail

.Lmla_norescale_B:
	v_exp_f32_e32 v64, v64
	v_exp_f32_e32 v65, v65
	v_exp_f32_e32 v66, v66
	v_exp_f32_e32 v67, v67
	v_exp_f32_e32 v68, v68
	v_exp_f32_e32 v69, v69
	v_exp_f32_e32 v70, v70
	v_exp_f32_e32 v71, v71
	v_cvt_pk_bf16_f32 v234, v64, v65
	v_cvt_pk_bf16_f32 v235, v66, v67
	v_cvt_pk_bf16_f32 v236, v68, v69
	v_cvt_pk_bf16_f32 v237, v70, v71
	v_exp_f32_e32 v72, v72
	v_exp_f32_e32 v73, v73
	v_exp_f32_e32 v74, v74
	v_exp_f32_e32 v75, v75
	v_exp_f32_e32 v76, v76
	v_exp_f32_e32 v77, v77
	v_exp_f32_e32 v78, v78
	v_exp_f32_e32 v79, v79
	v_cvt_pk_bf16_f32 v238, v72, v73
	v_cvt_pk_bf16_f32 v239, v74, v75
	v_cvt_pk_bf16_f32 v240, v76, v77
	v_cvt_pk_bf16_f32 v241, v78, v79
	v_exp_f32_e32 v48, v48
	v_exp_f32_e32 v49, v49
	v_exp_f32_e32 v50, v50
	v_exp_f32_e32 v51, v51
	v_exp_f32_e32 v52, v52
	v_exp_f32_e32 v53, v53
	v_exp_f32_e32 v54, v54
	v_exp_f32_e32 v55, v55
	v_cvt_pk_bf16_f32 v242, v48, v49
	v_cvt_pk_bf16_f32 v243, v50, v51
	v_cvt_pk_bf16_f32 v244, v52, v53
	v_cvt_pk_bf16_f32 v245, v54, v55
	v_exp_f32_e32 v56, v56
	v_exp_f32_e32 v57, v57
	v_exp_f32_e32 v58, v58
	v_exp_f32_e32 v59, v59
	v_exp_f32_e32 v60, v60
	v_exp_f32_e32 v61, v61
	v_exp_f32_e32 v62, v62
	v_exp_f32_e32 v63, v63
	v_cvt_pk_bf16_f32 v246, v56, v57
	v_cvt_pk_bf16_f32 v247, v58, v59
	v_cvt_pk_bf16_f32 v248, v60, v61
	v_cvt_pk_bf16_f32 v249, v62, v63
	v_add_f32_e32 v172, v64, v65
	v_add_f32_e32 v173, v66, v67
	v_add_f32_e32 v177, v68, v69
	v_add_f32_e32 v64, v70, v71
	v_add_f32_e32 v172, v172, v72
	v_add_f32_e32 v173, v173, v73
	v_add_f32_e32 v177, v177, v74
	v_add_f32_e32 v64, v64, v75
	v_add_f32_e32 v172, v172, v76
	v_add_f32_e32 v173, v173, v77
	v_add_f32_e32 v177, v177, v78
	v_add_f32_e32 v64, v64, v79
	v_add_f32_e32 v172, v172, v48
	v_add_f32_e32 v173, v173, v49
	v_add_f32_e32 v177, v177, v50
	v_add_f32_e32 v64, v64, v51
	v_add_f32_e32 v172, v172, v52
	v_add_f32_e32 v173, v173, v53
	v_add_f32_e32 v177, v177, v54
	v_add_f32_e32 v64, v64, v55
	v_add_f32_e32 v172, v172, v56
	v_add_f32_e32 v173, v173, v57
	v_add_f32_e32 v177, v177, v58
	v_add_f32_e32 v64, v64, v59
	v_add_f32_e32 v172, v172, v60
	v_add_f32_e32 v173, v173, v61
	v_add_f32_e32 v177, v177, v62
	v_add_f32_e32 v64, v64, v63
	v_add_f32_e32 v172, v172, v173
	v_add_f32_e32 v177, v177, v64
	v_add_f32_e32 v172, v172, v177
	v_add_f32_e32 v157, v157, v172
	s_mov_b32 s14, 0x41000000
	s_mov_b32 s15, 0
	s_and_b32 s12, s28, 1
	s_mul_i32 s13, s12, 0x3400
	v_add_u32_e32 v52, s13, v112
	ds_read_b128 v[48:51], v52
	ds_read_b128 v[122:125], v52 offset:6656
	ds_read_b128 v[118:121], v52 offset:32
	ds_read_b128 v[126:129], v52 offset:6688
	ds_read_b128 v[130:133], v52 offset:64
	ds_read_b128 v[138:141], v52 offset:6720
	ds_read_b128 v[134:137], v52 offset:96
	ds_read_b128 v[142:145], v52 offset:6752
	ds_read_b128 v[146:149], v52 offset:128
	ds_read_b128 v[194:197], v52 offset:6784
	ds_read_b128 v[178:181], v52 offset:160
	ds_read_b128 v[198:201], v52 offset:6816
	s_mul_i32 s13, s12, 0x2400
	v_add_u32_e32 v177, s13, v176
	s_setprio 3
	v_mfma_f32_32x32x16_bf16 v[16:31], v[202:205], v[234:237], v[16:31]
	v_mfma_f32_32x32x16_bf16 v[0:15], v[218:221], v[234:237], v[0:15]
	v_mfma_f32_32x32x16_bf16 v[16:31], v[206:209], v[238:241], v[16:31]
	v_mfma_f32_32x32x16_bf16 v[0:15], v[222:225], v[238:241], v[0:15]
	v_mfma_f32_32x32x16_bf16 v[16:31], v[210:213], v[242:245], v[16:31]
	v_mfma_f32_32x32x16_bf16 v[0:15], v[226:229], v[242:245], v[0:15]
	v_mfma_f32_32x32x16_bf16 v[16:31], v[214:217], v[246:249], v[16:31]
	v_mfma_f32_32x32x16_bf16 v[0:15], v[230:233], v[246:249], v[0:15]
	s_waitcnt lgkmcnt(11)
	v_mfma_f32_32x32x16_bf16 v[64:79], v[48:51], v[80:83], v[32:47]
	s_waitcnt lgkmcnt(10)
	v_mfma_f32_32x32x16_bf16 v[48:63], v[122:125], v[80:83], v[32:47]
	s_waitcnt lgkmcnt(9)
	v_mfma_f32_32x32x16_bf16 v[64:79], v[118:121], v[84:87], v[64:79]
	s_waitcnt lgkmcnt(8)
	v_mfma_f32_32x32x16_bf16 v[48:63], v[126:129], v[84:87], v[48:63]
	s_waitcnt lgkmcnt(7)
	v_mfma_f32_32x32x16_bf16 v[64:79], v[130:133], v[88:91], v[64:79]
	s_waitcnt lgkmcnt(6)
	v_mfma_f32_32x32x16_bf16 v[48:63], v[138:141], v[88:91], v[48:63]
	s_waitcnt lgkmcnt(5)
	v_mfma_f32_32x32x16_bf16 v[64:79], v[134:137], v[92:95], v[64:79]
	s_waitcnt lgkmcnt(4)
	v_mfma_f32_32x32x16_bf16 v[48:63], v[142:145], v[92:95], v[48:63]
	s_waitcnt lgkmcnt(3)
	v_mfma_f32_32x32x16_bf16 v[64:79], v[146:149], v[96:99], v[64:79]
	ds_read_b128 v[202:205], v177 offset:26624
	ds_read_b128 v[206:209], v177 offset:26656
	ds_read_b128 v[218:221], v177 offset:31232
	ds_read_b128 v[222:225], v177 offset:31264
	ds_read_b128 v[210:213], v177 offset:26688
	ds_read_b128 v[214:217], v177 offset:26720
	ds_read_b128 v[226:229], v177 offset:31296
	ds_read_b128 v[230:233], v177 offset:31328
	s_waitcnt lgkmcnt(10)
	v_mfma_f32_32x32x16_bf16 v[48:63], v[194:197], v[96:99], v[48:63]
	s_add_i32 s12, s28, 1
	s_cmp_ge_i32 s12, s22
	s_cbranch_scc1 .Lmla_nowrite_B
	s_and_b32 s12, s12, 1
	s_mul_i32 s13, s12, 0x3400
	v_add3_u32 v172, s13, v165, v166
	s_waitcnt vmcnt(0)
	ds_write_b128 v172, v[104:107]
	s_mulk_i32 s12, 0x2400
	v_add_u32_e32 v172, s12, v169
	v_add_u32_e32 v172, 0x6800, v172
	ds_write2_b64 v172, v[114:115], v[116:117] offset1:2
	s_add_i32 s12, s28, 2
	s_cmp_ge_i32 s12, s22
	s_cbranch_scc1 .Lmla_nowrite_B
	s_nop 1
	global_load_dwordx4 v[104:107], v[150:151], off
	global_load_dwordx4 v[114:117], v[152:153], off
	v_lshl_add_u64 v[150:151], v[150:151], 0, s[26:27]
	v_lshl_add_u64 v[152:153], v[152:153], 0, s[30:31]
.Lmla_nowrite_B:
	s_waitcnt lgkmcnt(9)
	v_mfma_f32_32x32x16_bf16 v[64:79], v[178:181], v[100:103], v[64:79]
	s_waitcnt lgkmcnt(8)
	v_mfma_f32_32x32x16_bf16 v[48:63], v[198:201], v[100:103], v[48:63]
	s_setprio 0
	s_waitcnt lgkmcnt(0)
	s_barrier
	s_add_i32 s28, s28, 1
	s_cmp_lt_i32 s28, s22
	s_cbranch_scc1 .Lmla_B_loop
